# S5 pass-2: the state-projection MFMAs of a chunk also moved into the next chunk's recurrence steps (LDS read latency and MFMA chain overlapped)
# speedup vs baseline: 1.0045x; 1.0011x over previous
.LBB0_873:
	v_mov_b32_e32 v224, 0x3d122279
	v_mov_b32_e32 v225, 0x3d122279
	v_mov_b32_e32 v226, 0x3f4c422a
	v_mov_b32_e32 v227, 0x3f4c422a
	v_mov_b32_e32 v228, 0xc038aa3b
	v_mov_b32_e32 v229, 0xc038aa3b
	v_mov_b32_e32 v230, 1.0
	v_mov_b32_e32 v231, 1.0
	v_cndmask_b32_e64 v93, v83, 0, s[10:11]
	v_cndmask_b32_e64 v92, v82, 0, s[10:11]
	v_cndmask_b32_e64 v91, v81, 0, s[10:11]
	v_cndmask_b32_e64 v90, v80, 0, s[10:11]
	v_add_u32_e32 v81, v139, v141
	v_add_u32_e32 v83, v139, v142
	v_mfma_f32_16x16x32_bf16 v[192:195], v[90:93], v[0:3], 0
	v_add_u32_e32 v88, v139, v143
	v_add_u32_e32 v82, s86, v140
	v_mov_b32_e32 v240, v86
	v_mov_b32_e32 v241, v87
	v_mfma_f32_16x16x32_bf16 v[196:199], v[90:93], v[4:7], 0
	v_mfma_f32_16x16x32_bf16 v[200:203], v[90:93], v[8:11], 0
	s_nop 2
	s_nop 2
	v_cndmask_b32_e64 v79, v79, 0, s[10:11]
	v_mfma_f32_16x16x32_bf16 v[204:207], v[90:93], v[12:15], 0
	v_cndmask_b32_e64 v78, v78, 0, s[10:11]
	v_cndmask_b32_e64 v77, v77, 0, s[10:11]
	v_cndmask_b32_e64 v76, v76, 0, s[10:11]
	v_mfma_f32_16x16x32_bf16 v[212:215], v[90:93], v[20:23], 0
	v_cndmask_b32_e64 v75, v75, 0, s[10:11]
	v_cndmask_b32_e64 v74, v74, 0, s[10:11]
	v_cndmask_b32_e64 v73, v73, 0, s[10:11]
	v_mfma_f32_16x16x32_bf16 v[208:211], v[90:93], v[16:19], 0
	s_nop 6
	v_mfma_f32_16x16x32_bf16 v[216:219], v[90:93], v[24:27], 0
	s_nop 6
	v_mfma_f32_16x16x32_bf16 v[220:223], v[90:93], v[28:31], 0
	v_cndmask_b32_e64 v72, v72, 0, s[10:11]
	v_cndmask_b32_e64 v71, v71, 0, s[10:11]
	v_cndmask_b32_e64 v70, v70, 0, s[10:11]
	v_mfma_f32_16x16x32_bf16 v[90:93], v[90:93], v[48:51], 0
	v_cndmask_b32_e64 v69, v69, 0, s[10:11]
	s_nop 2
	s_nop 7
	v_permlane16_swap_b32_e32 v192, v196
	v_permlane16_swap_b32_e32 v193, v197
	v_permlane16_swap_b32_e32 v194, v198
	v_permlane16_swap_b32_e32 v195, v199
	v_permlane16_swap_b32_e32 v200, v204
	v_permlane16_swap_b32_e32 v201, v205
	v_permlane16_swap_b32_e32 v202, v206
	v_permlane16_swap_b32_e32 v203, v207
	v_permlane16_swap_b32_e32 v208, v212
	v_permlane16_swap_b32_e32 v209, v213
	v_permlane16_swap_b32_e32 v210, v214
	v_permlane16_swap_b32_e32 v211, v215
	v_permlane16_swap_b32_e32 v216, v220
	v_permlane16_swap_b32_e32 v217, v221
	v_permlane16_swap_b32_e32 v218, v222
	v_permlane16_swap_b32_e32 v219, v223
	v_permlane32_swap_b32_e32 v192, v200
	v_permlane32_swap_b32_e32 v193, v201
	v_permlane32_swap_b32_e32 v194, v202
	v_permlane32_swap_b32_e32 v195, v203
	v_permlane32_swap_b32_e32 v196, v204
	v_permlane32_swap_b32_e32 v197, v205
	v_permlane32_swap_b32_e32 v198, v206
	v_permlane32_swap_b32_e32 v199, v207
	v_permlane32_swap_b32_e32 v208, v216
	v_permlane32_swap_b32_e32 v209, v217
	v_permlane32_swap_b32_e32 v210, v218
	v_permlane32_swap_b32_e32 v211, v219
	v_permlane32_swap_b32_e32 v212, v220
	v_permlane32_swap_b32_e32 v213, v221
	v_permlane32_swap_b32_e32 v214, v222
	v_permlane32_swap_b32_e32 v215, v223
	v_fma_f32 v242, -v132, v241, v192
	v_fma_f32 v243, v132, v240, v208
	v_fma_f32 v244, v128, v240, v242
	v_fma_f32 v245, v128, v241, v243
	v_cvt_pk_bf16_f32 v248, v244, v245
	ds_write_b32 v149, v248 offset:10240
	v_fma_f32 v242, -v132, v245, v193
	v_fma_f32 v243, v132, v244, v209
	v_fma_f32 v246, v128, v244, v242
	v_fma_f32 v247, v128, v245, v243
	v_cvt_pk_bf16_f32 v249, v246, v247
	ds_write_b32 v149, v249 offset:10512
	v_fma_f32 v242, -v132, v247, v194
	v_fma_f32 v243, v132, v246, v210
	v_fma_f32 v244, v128, v246, v242
	v_fma_f32 v245, v128, v247, v243
	v_cvt_pk_bf16_f32 v248, v244, v245
	ds_write_b32 v149, v248 offset:10784
	v_fma_f32 v242, -v132, v245, v195
	v_fma_f32 v243, v132, v244, v211
	v_fma_f32 v246, v128, v244, v242
	v_fma_f32 v247, v128, v245, v243
	v_cvt_pk_bf16_f32 v249, v246, v247
	ds_write_b32 v149, v249 offset:11056
	v_fma_f32 v242, -v132, v247, v196
	v_fma_f32 v243, v132, v246, v212
	v_fma_f32 v244, v128, v246, v242
	v_fma_f32 v245, v128, v247, v243
	v_cvt_pk_bf16_f32 v248, v244, v245
	ds_write_b32 v149, v248 offset:11328
	v_fma_f32 v242, -v132, v245, v197
	v_fma_f32 v243, v132, v244, v213
	v_fma_f32 v246, v128, v244, v242
	v_fma_f32 v247, v128, v245, v243
	v_cvt_pk_bf16_f32 v249, v246, v247
	ds_write_b32 v149, v249 offset:11600
	v_fma_f32 v242, -v132, v247, v198
	v_fma_f32 v243, v132, v246, v214
	v_fma_f32 v244, v128, v246, v242
	v_fma_f32 v245, v128, v247, v243
	v_cvt_pk_bf16_f32 v248, v244, v245
	ds_write_b32 v149, v248 offset:11872
	v_fma_f32 v242, -v132, v245, v199
	v_fma_f32 v243, v132, v244, v215
	v_fma_f32 v246, v128, v244, v242
	v_fma_f32 v247, v128, v245, v243
	v_cvt_pk_bf16_f32 v249, v246, v247
	ds_write_b32 v149, v249 offset:12144
	v_fma_f32 v242, -v132, v247, v200
	v_fma_f32 v243, v132, v246, v216
	v_fma_f32 v244, v128, v246, v242
	v_fma_f32 v245, v128, v247, v243
	v_cvt_pk_bf16_f32 v248, v244, v245
	ds_write_b32 v149, v248 offset:12416
	v_fma_f32 v242, -v132, v245, v201
	v_fma_f32 v243, v132, v244, v217
	v_fma_f32 v246, v128, v244, v242
	v_fma_f32 v247, v128, v245, v243
	v_cvt_pk_bf16_f32 v249, v246, v247
	ds_write_b32 v149, v249 offset:12688
	v_fma_f32 v242, -v132, v247, v202
	v_fma_f32 v243, v132, v246, v218
	v_fma_f32 v244, v128, v246, v242
	v_fma_f32 v245, v128, v247, v243
	v_cvt_pk_bf16_f32 v248, v244, v245
	ds_write_b32 v149, v248 offset:12960
	v_fma_f32 v242, -v132, v245, v203
	v_fma_f32 v243, v132, v244, v219
	v_fma_f32 v246, v128, v244, v242
	v_fma_f32 v247, v128, v245, v243
	v_cvt_pk_bf16_f32 v249, v246, v247
	ds_write_b32 v149, v249 offset:13232
	v_fma_f32 v242, -v132, v247, v204
	v_fma_f32 v243, v132, v246, v220
	v_fma_f32 v244, v128, v246, v242
	v_fma_f32 v245, v128, v247, v243
	v_cvt_pk_bf16_f32 v248, v244, v245
	ds_write_b32 v149, v248 offset:13504
	v_fma_f32 v242, -v132, v245, v205
	v_fma_f32 v243, v132, v244, v221
	v_fma_f32 v246, v128, v244, v242
	v_fma_f32 v247, v128, v245, v243
	v_cvt_pk_bf16_f32 v249, v246, v247
	ds_write_b32 v149, v249 offset:13776
	v_fma_f32 v242, -v132, v247, v206
	v_fma_f32 v243, v132, v246, v222
	v_fma_f32 v244, v128, v246, v242
	v_fma_f32 v245, v128, v247, v243
	v_cvt_pk_bf16_f32 v248, v244, v245
	ds_write_b32 v149, v248 offset:14048
	v_fma_f32 v242, -v132, v245, v207
	v_fma_f32 v243, v132, v244, v223
	v_fma_f32 v87, v128, v244, v242
	v_fma_f32 v86, v128, v245, v243
	v_cvt_pk_bf16_f32 v249, v87, v86
	ds_write_b32 v149, v249 offset:14320
	s_waitcnt lgkmcnt(0)
	v_add_u32_e32 v80, v150, v138
	ds_read_b128 v[94:97], v80 offset:10240
	ds_read_b128 v[98:101], v80 offset:10304
	ds_read_b128 v[184:187], v80 offset:10368
	ds_read_b128 v[188:191], v80 offset:10432
	v_cndmask_b32_e64 v68, v68, 0, s[10:11]
	s_add_u32 s30, s30, 0x40000
	s_addc_u32 s31, s31, 0
	s_cmp_eq_u32 s30, 0x240000
	s_cselect_b64 s[34:35], -1, 0
	v_mfma_f32_16x16x32_bf16 v[196:199], v[76:79], v[4:7], 0
	v_mfma_f32_16x16x32_bf16 v[200:203], v[76:79], v[8:11], 0
	s_nop 5
	v_mfma_f32_16x16x32_bf16 v[204:207], v[76:79], v[12:15], 0
	v_mfma_f32_16x16x32_bf16 v[192:195], v[76:79], v[0:3], 0
	v_mfma_f32_16x16x32_bf16 v[208:211], v[76:79], v[16:19], 0
	s_nop 0
	s_nop 3
	v_mfma_f32_16x16x32_bf16 v[212:215], v[76:79], v[20:23], 0
	v_mov_b32_e32 v240, v87
	v_mov_b32_e32 v241, v86
	v_mfma_f32_16x16x32_bf16 v[216:219], v[76:79], v[24:27], 0
	s_nop 0
	s_nop 4
	v_mfma_f32_16x16x32_bf16 v[220:223], v[76:79], v[28:31], 0
	v_mfma_f32_16x16x32_bf16 v[76:79], v[76:79], v[48:51], 0
	s_nop 5
	s_nop 7
	v_permlane16_swap_b32_e32 v192, v196
	v_permlane16_swap_b32_e32 v193, v197
	v_permlane16_swap_b32_e32 v194, v198
	v_permlane16_swap_b32_e32 v195, v199
	v_permlane16_swap_b32_e32 v200, v204
	v_permlane16_swap_b32_e32 v201, v205
	v_permlane16_swap_b32_e32 v202, v206
	v_permlane16_swap_b32_e32 v203, v207
	v_permlane16_swap_b32_e32 v208, v212
	v_permlane16_swap_b32_e32 v209, v213
	v_permlane16_swap_b32_e32 v210, v214
	v_permlane16_swap_b32_e32 v211, v215
	v_permlane16_swap_b32_e32 v216, v220
	v_permlane16_swap_b32_e32 v217, v221
	v_permlane16_swap_b32_e32 v218, v222
	v_permlane16_swap_b32_e32 v219, v223
	v_permlane32_swap_b32_e32 v192, v200
	v_permlane32_swap_b32_e32 v193, v201
	v_permlane32_swap_b32_e32 v194, v202
	v_permlane32_swap_b32_e32 v195, v203
	v_permlane32_swap_b32_e32 v196, v204
	v_permlane32_swap_b32_e32 v197, v205
	v_permlane32_swap_b32_e32 v198, v206
	v_permlane32_swap_b32_e32 v199, v207
	v_permlane32_swap_b32_e32 v208, v216
	v_permlane32_swap_b32_e32 v209, v217
	v_permlane32_swap_b32_e32 v210, v218
	v_permlane32_swap_b32_e32 v211, v219
	v_permlane32_swap_b32_e32 v212, v220
	v_permlane32_swap_b32_e32 v213, v221
	v_permlane32_swap_b32_e32 v214, v222
	v_permlane32_swap_b32_e32 v215, v223
	v_fma_f32 v242, -v132, v241, v192
	v_fma_f32 v243, v132, v240, v208
	v_fma_f32 v244, v128, v240, v242
	v_fma_f32 v245, v128, v241, v243
	v_cvt_pk_bf16_f32 v248, v244, v245
	ds_write_b32 v149, v248 offset:10240
	s_waitcnt lgkmcnt(4)
	v_mfma_f32_16x16x32_bf16 v[90:93], v[94:97], v[32:35], v[90:93]
	v_fma_f32 v242, -v132, v245, v193
	v_fma_f32 v243, v132, v244, v209
	v_fma_f32 v246, v128, v244, v242
	v_fma_f32 v247, v128, v245, v243
	v_cvt_pk_bf16_f32 v249, v246, v247
	ds_write_b32 v149, v249 offset:10512
	s_waitcnt lgkmcnt(4)
	v_mfma_f32_16x16x32_bf16 v[90:93], v[98:101], v[36:39], v[90:93]
	v_fma_f32 v242, -v132, v247, v194
	v_fma_f32 v243, v132, v246, v210
	v_fma_f32 v244, v128, v246, v242
	v_fma_f32 v245, v128, v247, v243
	v_cvt_pk_bf16_f32 v248, v244, v245
	ds_write_b32 v149, v248 offset:10784
	s_waitcnt lgkmcnt(4)
	v_mfma_f32_16x16x32_bf16 v[90:93], v[184:187], v[40:43], v[90:93]
	v_fma_f32 v242, -v132, v245, v195
	v_fma_f32 v243, v132, v244, v211
	v_fma_f32 v246, v128, v244, v242
	v_fma_f32 v247, v128, v245, v243
	v_cvt_pk_bf16_f32 v249, v246, v247
	ds_write_b32 v149, v249 offset:11056
	s_waitcnt lgkmcnt(4)
	v_mfma_f32_16x16x32_bf16 v[90:93], v[188:191], v[44:47], v[90:93]
	v_fma_f32 v242, -v132, v247, v196
	v_fma_f32 v243, v132, v246, v212
	v_fma_f32 v244, v128, v246, v242
	v_fma_f32 v245, v128, v247, v243
	v_cvt_pk_bf16_f32 v248, v244, v245
	ds_write_b32 v149, v248 offset:11328
	v_fma_f32 v242, -v132, v245, v197
	v_fma_f32 v243, v132, v244, v213
	v_fma_f32 v246, v128, v244, v242
	v_fma_f32 v247, v128, v245, v243
	v_cvt_pk_bf16_f32 v249, v246, v247
	ds_write_b32 v149, v249 offset:11600
	v_fma_f32 v242, -v132, v247, v198
	v_fma_f32 v243, v132, v246, v214
	v_fma_f32 v244, v128, v246, v242
	v_fma_f32 v245, v128, v247, v243
	v_cvt_pk_bf16_f32 v248, v244, v245
	ds_write_b32 v149, v248 offset:11872
	v_pk_mul_f32 v[232:233], v[90:91], v[224:225]
	v_pk_mul_f32 v[234:235], v[92:93], v[224:225]
	v_pk_fma_f32 v[232:233], v[90:91], v[232:233], v[226:227]
	v_fma_f32 v242, -v132, v245, v199
	v_fma_f32 v243, v132, v244, v215
	v_fma_f32 v246, v128, v244, v242
	v_fma_f32 v247, v128, v245, v243
	v_cvt_pk_bf16_f32 v249, v246, v247
	ds_write_b32 v149, v249 offset:12144
	v_pk_fma_f32 v[234:235], v[92:93], v[234:235], v[226:227]
	v_pk_mul_f32 v[232:233], v[90:91], v[232:233]
	v_pk_mul_f32 v[234:235], v[92:93], v[234:235]
	v_fma_f32 v242, -v132, v247, v200
	v_fma_f32 v243, v132, v246, v216
	v_fma_f32 v244, v128, v246, v242
	v_fma_f32 v245, v128, v247, v243
	v_cvt_pk_bf16_f32 v248, v244, v245
	ds_write_b32 v149, v248 offset:12416
	v_pk_mul_f32 v[232:233], v[232:233], v[228:229]
	v_pk_mul_f32 v[234:235], v[234:235], v[228:229]
	v_exp_f32_e32 v232, v232
	v_fma_f32 v242, -v132, v245, v201
	v_fma_f32 v243, v132, v244, v217
	v_fma_f32 v246, v128, v244, v242
	v_fma_f32 v247, v128, v245, v243
	v_cvt_pk_bf16_f32 v249, v246, v247
	ds_write_b32 v149, v249 offset:12688
	v_exp_f32_e32 v233, v233
	v_exp_f32_e32 v234, v234
	v_exp_f32_e32 v235, v235
	v_fma_f32 v242, -v132, v247, v202
	v_fma_f32 v243, v132, v246, v218
	v_fma_f32 v244, v128, v246, v242
	v_fma_f32 v245, v128, v247, v243
	v_cvt_pk_bf16_f32 v248, v244, v245
	ds_write_b32 v149, v248 offset:12960
	v_pk_add_f32 v[232:233], v[232:233], v[230:231]
	v_pk_add_f32 v[234:235], v[234:235], v[230:231]
	v_rcp_f32_e32 v232, v232
	v_fma_f32 v242, -v132, v245, v203
	v_fma_f32 v243, v132, v244, v219
	v_fma_f32 v246, v128, v244, v242
	v_fma_f32 v247, v128, v245, v243
	v_cvt_pk_bf16_f32 v249, v246, v247
	ds_write_b32 v149, v249 offset:13232
	v_rcp_f32_e32 v233, v233
	v_rcp_f32_e32 v234, v234
	v_rcp_f32_e32 v235, v235
	v_fma_f32 v242, -v132, v247, v204
	v_fma_f32 v243, v132, v246, v220
	v_fma_f32 v244, v128, v246, v242
	v_fma_f32 v245, v128, v247, v243
	v_cvt_pk_bf16_f32 v248, v244, v245
	ds_write_b32 v149, v248 offset:13504
	v_pk_mul_f32 v[232:233], v[90:91], v[232:233]
	v_pk_mul_f32 v[234:235], v[92:93], v[234:235]
	v_cvt_pk_bf16_f32 v236, v232, v232
	v_fma_f32 v242, -v132, v245, v205
	v_fma_f32 v243, v132, v244, v221
	v_fma_f32 v246, v128, v244, v242
	v_fma_f32 v247, v128, v245, v243
	v_cvt_pk_bf16_f32 v249, v246, v247
	ds_write_b32 v149, v249 offset:13776
	v_cvt_pk_bf16_f32 v237, v233, v233
	v_cvt_pk_bf16_f32 v238, v234, v234
	v_cvt_pk_bf16_f32 v239, v235, v235
	v_fma_f32 v242, -v132, v247, v206
	v_fma_f32 v243, v132, v246, v222
	v_fma_f32 v244, v128, v246, v242
	v_fma_f32 v245, v128, v247, v243
	v_cvt_pk_bf16_f32 v248, v244, v245
	ds_write_b32 v149, v248 offset:14048
	ds_write_b16 v160, v236 offset:14592
	ds_write_b16 v160, v237 offset:14624
	ds_write_b16 v160, v238 offset:14656
	v_fma_f32 v242, -v132, v245, v207
	v_fma_f32 v243, v132, v244, v223
	v_fma_f32 v87, v128, v244, v242
	v_fma_f32 v86, v128, v245, v243
	v_cvt_pk_bf16_f32 v249, v87, v86
	ds_write_b32 v149, v249 offset:14320
	ds_write_b16 v161, v239 offset:14592
	s_waitcnt lgkmcnt(0)
	ds_read_b128 v[90:93], v80 offset:10240
	ds_read_b128 v[94:97], v80 offset:10304
	ds_read_b128 v[184:187], v80 offset:10368
	ds_read_b128 v[188:191], v80 offset:10432
	v_mfma_f32_16x16x32_bf16 v[196:199], v[72:75], v[4:7], 0
	v_mfma_f32_16x16x32_bf16 v[200:203], v[72:75], v[8:11], 0
	s_nop 5
	v_mfma_f32_16x16x32_bf16 v[204:207], v[72:75], v[12:15], 0
	v_mfma_f32_16x16x32_bf16 v[192:195], v[72:75], v[0:3], 0
	v_mfma_f32_16x16x32_bf16 v[208:211], v[72:75], v[16:19], 0
	s_nop 0
	s_nop 3
	v_mfma_f32_16x16x32_bf16 v[212:215], v[72:75], v[20:23], 0
	v_mov_b32_e32 v240, v87
	v_mov_b32_e32 v241, v86
	v_mfma_f32_16x16x32_bf16 v[216:219], v[72:75], v[24:27], 0
	s_nop 0
	s_nop 4
	v_mfma_f32_16x16x32_bf16 v[220:223], v[72:75], v[28:31], 0
	v_mfma_f32_16x16x32_bf16 v[72:75], v[72:75], v[48:51], 0
	s_nop 5
	s_nop 7
	v_permlane16_swap_b32_e32 v192, v196
	v_permlane16_swap_b32_e32 v193, v197
	v_permlane16_swap_b32_e32 v194, v198
	v_permlane16_swap_b32_e32 v195, v199
	v_permlane16_swap_b32_e32 v200, v204
	v_permlane16_swap_b32_e32 v201, v205
	v_permlane16_swap_b32_e32 v202, v206
	v_permlane16_swap_b32_e32 v203, v207
	v_permlane16_swap_b32_e32 v208, v212
	v_permlane16_swap_b32_e32 v209, v213
	v_permlane16_swap_b32_e32 v210, v214
	v_permlane16_swap_b32_e32 v211, v215
	v_permlane16_swap_b32_e32 v216, v220
	v_permlane16_swap_b32_e32 v217, v221
	v_permlane16_swap_b32_e32 v218, v222
	v_permlane16_swap_b32_e32 v219, v223
	v_permlane32_swap_b32_e32 v192, v200
	v_permlane32_swap_b32_e32 v193, v201
	v_permlane32_swap_b32_e32 v194, v202
	v_permlane32_swap_b32_e32 v195, v203
	v_permlane32_swap_b32_e32 v196, v204
	v_permlane32_swap_b32_e32 v197, v205
	v_permlane32_swap_b32_e32 v198, v206
	v_permlane32_swap_b32_e32 v199, v207
	v_permlane32_swap_b32_e32 v208, v216
	v_permlane32_swap_b32_e32 v209, v217
	v_permlane32_swap_b32_e32 v210, v218
	v_permlane32_swap_b32_e32 v211, v219
	v_permlane32_swap_b32_e32 v212, v220
	v_permlane32_swap_b32_e32 v213, v221
	v_permlane32_swap_b32_e32 v214, v222
	v_permlane32_swap_b32_e32 v215, v223
	v_fma_f32 v242, -v132, v241, v192
	v_fma_f32 v243, v132, v240, v208
	v_fma_f32 v244, v128, v240, v242
	v_fma_f32 v245, v128, v241, v243
	v_cvt_pk_bf16_f32 v248, v244, v245
	ds_write_b32 v149, v248 offset:10240
	s_waitcnt lgkmcnt(4)
	v_mfma_f32_16x16x32_bf16 v[76:79], v[90:93], v[32:35], v[76:79]
	v_fma_f32 v242, -v132, v245, v193
	v_fma_f32 v243, v132, v244, v209
	v_fma_f32 v246, v128, v244, v242
	v_fma_f32 v247, v128, v245, v243
	v_cvt_pk_bf16_f32 v249, v246, v247
	ds_write_b32 v149, v249 offset:10512
	s_waitcnt lgkmcnt(4)
	v_mfma_f32_16x16x32_bf16 v[76:79], v[94:97], v[36:39], v[76:79]
	v_fma_f32 v242, -v132, v247, v194
	v_fma_f32 v243, v132, v246, v210
	v_fma_f32 v244, v128, v246, v242
	v_fma_f32 v245, v128, v247, v243
	v_cvt_pk_bf16_f32 v248, v244, v245
	ds_write_b32 v149, v248 offset:10784
	s_waitcnt lgkmcnt(4)
	v_mfma_f32_16x16x32_bf16 v[76:79], v[184:187], v[40:43], v[76:79]
	v_fma_f32 v242, -v132, v245, v195
	v_fma_f32 v243, v132, v244, v211
	v_fma_f32 v246, v128, v244, v242
	v_fma_f32 v247, v128, v245, v243
	v_cvt_pk_bf16_f32 v249, v246, v247
	ds_write_b32 v149, v249 offset:11056
	s_waitcnt lgkmcnt(4)
	v_mfma_f32_16x16x32_bf16 v[76:79], v[188:191], v[44:47], v[76:79]
	v_fma_f32 v242, -v132, v247, v196
	v_fma_f32 v243, v132, v246, v212
	v_fma_f32 v244, v128, v246, v242
	v_fma_f32 v245, v128, v247, v243
	v_cvt_pk_bf16_f32 v248, v244, v245
	ds_write_b32 v149, v248 offset:11328
	v_fma_f32 v242, -v132, v245, v197
	v_fma_f32 v243, v132, v244, v213
	v_fma_f32 v246, v128, v244, v242
	v_fma_f32 v247, v128, v245, v243
	v_cvt_pk_bf16_f32 v249, v246, v247
	ds_write_b32 v149, v249 offset:11600
	v_fma_f32 v242, -v132, v247, v198
	v_fma_f32 v243, v132, v246, v214
	v_fma_f32 v244, v128, v246, v242
	v_fma_f32 v245, v128, v247, v243
	v_cvt_pk_bf16_f32 v248, v244, v245
	ds_write_b32 v149, v248 offset:11872
	v_pk_mul_f32 v[232:233], v[76:77], v[224:225]
	v_pk_mul_f32 v[234:235], v[78:79], v[224:225]
	v_pk_fma_f32 v[232:233], v[76:77], v[232:233], v[226:227]
	v_fma_f32 v242, -v132, v245, v199
	v_fma_f32 v243, v132, v244, v215
	v_fma_f32 v246, v128, v244, v242
	v_fma_f32 v247, v128, v245, v243
	v_cvt_pk_bf16_f32 v249, v246, v247
	ds_write_b32 v149, v249 offset:12144
	v_pk_fma_f32 v[234:235], v[78:79], v[234:235], v[226:227]
	v_pk_mul_f32 v[232:233], v[76:77], v[232:233]
	v_pk_mul_f32 v[234:235], v[78:79], v[234:235]
	v_fma_f32 v242, -v132, v247, v200
	v_fma_f32 v243, v132, v246, v216
	v_fma_f32 v244, v128, v246, v242
	v_fma_f32 v245, v128, v247, v243
	v_cvt_pk_bf16_f32 v248, v244, v245
	ds_write_b32 v149, v248 offset:12416
	v_pk_mul_f32 v[232:233], v[232:233], v[228:229]
	v_pk_mul_f32 v[234:235], v[234:235], v[228:229]
	v_exp_f32_e32 v232, v232
	v_fma_f32 v242, -v132, v245, v201
	v_fma_f32 v243, v132, v244, v217
	v_fma_f32 v246, v128, v244, v242
	v_fma_f32 v247, v128, v245, v243
	v_cvt_pk_bf16_f32 v249, v246, v247
	ds_write_b32 v149, v249 offset:12688
	v_exp_f32_e32 v233, v233
	v_exp_f32_e32 v234, v234
	v_exp_f32_e32 v235, v235
	v_fma_f32 v242, -v132, v247, v202
	v_fma_f32 v243, v132, v246, v218
	v_fma_f32 v244, v128, v246, v242
	v_fma_f32 v245, v128, v247, v243
	v_cvt_pk_bf16_f32 v248, v244, v245
	ds_write_b32 v149, v248 offset:12960
	v_pk_add_f32 v[232:233], v[232:233], v[230:231]
	v_pk_add_f32 v[234:235], v[234:235], v[230:231]
	v_rcp_f32_e32 v232, v232
	v_fma_f32 v242, -v132, v245, v203
	v_fma_f32 v243, v132, v244, v219
	v_fma_f32 v246, v128, v244, v242
	v_fma_f32 v247, v128, v245, v243
	v_cvt_pk_bf16_f32 v249, v246, v247
	ds_write_b32 v149, v249 offset:13232
	v_rcp_f32_e32 v233, v233
	v_rcp_f32_e32 v234, v234
	v_rcp_f32_e32 v235, v235
	v_fma_f32 v242, -v132, v247, v204
	v_fma_f32 v243, v132, v246, v220
	v_fma_f32 v244, v128, v246, v242
	v_fma_f32 v245, v128, v247, v243
	v_cvt_pk_bf16_f32 v248, v244, v245
	ds_write_b32 v149, v248 offset:13504
	v_pk_mul_f32 v[232:233], v[76:77], v[232:233]
	v_pk_mul_f32 v[234:235], v[78:79], v[234:235]
	v_cvt_pk_bf16_f32 v236, v232, v232
	v_fma_f32 v242, -v132, v245, v205
	v_fma_f32 v243, v132, v244, v221
	v_fma_f32 v246, v128, v244, v242
	v_fma_f32 v247, v128, v245, v243
	v_cvt_pk_bf16_f32 v249, v246, v247
	ds_write_b32 v149, v249 offset:13776
	v_cvt_pk_bf16_f32 v237, v233, v233
	v_cvt_pk_bf16_f32 v238, v234, v234
	v_cvt_pk_bf16_f32 v239, v235, v235
	v_fma_f32 v242, -v132, v247, v206
	v_fma_f32 v243, v132, v246, v222
	v_fma_f32 v244, v128, v246, v242
	v_fma_f32 v245, v128, v247, v243
	v_cvt_pk_bf16_f32 v248, v244, v245
	ds_write_b32 v149, v248 offset:14048
	ds_write_b16 v160, v236 offset:15104
	ds_write_b16 v160, v237 offset:15136
	ds_write_b16 v160, v238 offset:15168
	v_fma_f32 v242, -v132, v245, v207
	v_fma_f32 v243, v132, v244, v223
	v_fma_f32 v110, v128, v244, v242
	v_fma_f32 v111, v128, v245, v243
	v_cvt_pk_bf16_f32 v249, v110, v111
	ds_write_b32 v149, v249 offset:14320
	ds_write_b16 v162, v239 offset:14592
	s_waitcnt lgkmcnt(0)
	ds_read_b128 v[76:79], v80 offset:10240
	ds_read_b128 v[90:93], v80 offset:10304
	ds_read_b128 v[184:187], v80 offset:10368
	ds_read_b128 v[188:191], v80 offset:10432
	v_mfma_f32_16x16x32_bf16 v[196:199], v[68:71], v[4:7], 0
	v_mfma_f32_16x16x32_bf16 v[200:203], v[68:71], v[8:11], 0
	s_nop 5
	v_mfma_f32_16x16x32_bf16 v[204:207], v[68:71], v[12:15], 0
	v_mfma_f32_16x16x32_bf16 v[192:195], v[68:71], v[0:3], 0
	v_mfma_f32_16x16x32_bf16 v[208:211], v[68:71], v[16:19], 0
	s_nop 0
	s_nop 3
	v_mfma_f32_16x16x32_bf16 v[212:215], v[68:71], v[20:23], 0
	v_mfma_f32_16x16x32_bf16 v[216:219], v[68:71], v[24:27], 0
	s_nop 2
	s_nop 2
	v_mov_b32_e32 v240, v110
	v_mov_b32_e32 v241, v111
	v_mfma_f32_16x16x32_bf16 v[220:223], v[68:71], v[28:31], 0
	v_mfma_f32_16x16x32_bf16 v[68:71], v[68:71], v[48:51], 0
	s_nop 5
	s_nop 7
	v_permlane16_swap_b32_e32 v192, v196
	v_permlane16_swap_b32_e32 v193, v197
	v_permlane16_swap_b32_e32 v194, v198
	v_permlane16_swap_b32_e32 v195, v199
	v_permlane16_swap_b32_e32 v200, v204
	v_permlane16_swap_b32_e32 v201, v205
	v_permlane16_swap_b32_e32 v202, v206
	v_permlane16_swap_b32_e32 v203, v207
	v_permlane16_swap_b32_e32 v208, v212
	v_permlane16_swap_b32_e32 v209, v213
	v_permlane16_swap_b32_e32 v210, v214
	v_permlane16_swap_b32_e32 v211, v215
	v_permlane16_swap_b32_e32 v216, v220
	v_permlane16_swap_b32_e32 v217, v221
	v_permlane16_swap_b32_e32 v218, v222
	v_permlane16_swap_b32_e32 v219, v223
	v_permlane32_swap_b32_e32 v192, v200
	v_permlane32_swap_b32_e32 v193, v201
	v_permlane32_swap_b32_e32 v194, v202
	v_permlane32_swap_b32_e32 v195, v203
	v_permlane32_swap_b32_e32 v196, v204
	v_permlane32_swap_b32_e32 v197, v205
	v_permlane32_swap_b32_e32 v198, v206
	v_permlane32_swap_b32_e32 v199, v207
	v_permlane32_swap_b32_e32 v208, v216
	v_permlane32_swap_b32_e32 v209, v217
	v_permlane32_swap_b32_e32 v210, v218
	v_permlane32_swap_b32_e32 v211, v219
	v_permlane32_swap_b32_e32 v212, v220
	v_permlane32_swap_b32_e32 v213, v221
	v_permlane32_swap_b32_e32 v214, v222
	v_permlane32_swap_b32_e32 v215, v223
	v_fma_f32 v242, -v132, v241, v192
	v_fma_f32 v243, v132, v240, v208
	v_fma_f32 v244, v128, v240, v242
	v_fma_f32 v245, v128, v241, v243
	v_cvt_pk_bf16_f32 v248, v244, v245
	ds_write_b32 v149, v248 offset:10240
	s_waitcnt lgkmcnt(4)
	v_mfma_f32_16x16x32_bf16 v[72:75], v[76:79], v[32:35], v[72:75]
	v_fma_f32 v242, -v132, v245, v193
	v_fma_f32 v243, v132, v244, v209
	v_fma_f32 v246, v128, v244, v242
	v_fma_f32 v247, v128, v245, v243
	v_cvt_pk_bf16_f32 v249, v246, v247
	ds_write_b32 v149, v249 offset:10512
	s_waitcnt lgkmcnt(4)
	v_mfma_f32_16x16x32_bf16 v[72:75], v[90:93], v[36:39], v[72:75]
	v_fma_f32 v242, -v132, v247, v194
	v_fma_f32 v243, v132, v246, v210
	v_fma_f32 v244, v128, v246, v242
	v_fma_f32 v245, v128, v247, v243
	v_cvt_pk_bf16_f32 v248, v244, v245
	ds_write_b32 v149, v248 offset:10784
	s_waitcnt lgkmcnt(4)
	v_mfma_f32_16x16x32_bf16 v[72:75], v[184:187], v[40:43], v[72:75]
	v_fma_f32 v242, -v132, v245, v195
	v_fma_f32 v243, v132, v244, v211
	v_fma_f32 v246, v128, v244, v242
	v_fma_f32 v247, v128, v245, v243
	v_cvt_pk_bf16_f32 v249, v246, v247
	ds_write_b32 v149, v249 offset:11056
	s_waitcnt lgkmcnt(4)
	v_mfma_f32_16x16x32_bf16 v[72:75], v[188:191], v[44:47], v[72:75]
	v_fma_f32 v242, -v132, v247, v196
	v_fma_f32 v243, v132, v246, v212
	v_fma_f32 v244, v128, v246, v242
	v_fma_f32 v245, v128, v247, v243
	v_cvt_pk_bf16_f32 v248, v244, v245
	ds_write_b32 v149, v248 offset:11328
	v_fma_f32 v242, -v132, v245, v197
	v_fma_f32 v243, v132, v244, v213
	v_fma_f32 v246, v128, v244, v242
	v_fma_f32 v247, v128, v245, v243
	v_cvt_pk_bf16_f32 v249, v246, v247
	ds_write_b32 v149, v249 offset:11600
	v_fma_f32 v242, -v132, v247, v198
	v_fma_f32 v243, v132, v246, v214
	v_fma_f32 v244, v128, v246, v242
	v_fma_f32 v245, v128, v247, v243
	v_cvt_pk_bf16_f32 v248, v244, v245
	ds_write_b32 v149, v248 offset:11872
	v_pk_mul_f32 v[232:233], v[72:73], v[224:225]
	v_pk_mul_f32 v[234:235], v[74:75], v[224:225]
	v_pk_fma_f32 v[232:233], v[72:73], v[232:233], v[226:227]
	v_fma_f32 v242, -v132, v245, v199
	v_fma_f32 v243, v132, v244, v215
	v_fma_f32 v246, v128, v244, v242
	v_fma_f32 v247, v128, v245, v243
	v_cvt_pk_bf16_f32 v249, v246, v247
	ds_write_b32 v149, v249 offset:12144
	v_pk_fma_f32 v[234:235], v[74:75], v[234:235], v[226:227]
	v_pk_mul_f32 v[232:233], v[72:73], v[232:233]
	v_pk_mul_f32 v[234:235], v[74:75], v[234:235]
	v_fma_f32 v242, -v132, v247, v200
	v_fma_f32 v243, v132, v246, v216
	v_fma_f32 v244, v128, v246, v242
	v_fma_f32 v245, v128, v247, v243
	v_cvt_pk_bf16_f32 v248, v244, v245
	ds_write_b32 v149, v248 offset:12416
	v_pk_mul_f32 v[232:233], v[232:233], v[228:229]
	v_pk_mul_f32 v[234:235], v[234:235], v[228:229]
	v_exp_f32_e32 v232, v232
	v_fma_f32 v242, -v132, v245, v201
	v_fma_f32 v243, v132, v244, v217
	v_fma_f32 v246, v128, v244, v242
	v_fma_f32 v247, v128, v245, v243
	v_cvt_pk_bf16_f32 v249, v246, v247
	ds_write_b32 v149, v249 offset:12688
	v_exp_f32_e32 v233, v233
	v_exp_f32_e32 v234, v234
	v_exp_f32_e32 v235, v235
	v_fma_f32 v242, -v132, v247, v202
	v_fma_f32 v243, v132, v246, v218
	v_fma_f32 v244, v128, v246, v242
	v_fma_f32 v245, v128, v247, v243
	v_cvt_pk_bf16_f32 v248, v244, v245
	ds_write_b32 v149, v248 offset:12960
	v_pk_add_f32 v[232:233], v[232:233], v[230:231]
	v_pk_add_f32 v[234:235], v[234:235], v[230:231]
	v_rcp_f32_e32 v232, v232
	v_fma_f32 v242, -v132, v245, v203
	v_fma_f32 v243, v132, v244, v219
	v_fma_f32 v246, v128, v244, v242
	v_fma_f32 v247, v128, v245, v243
	v_cvt_pk_bf16_f32 v249, v246, v247
	ds_write_b32 v149, v249 offset:13232
	v_rcp_f32_e32 v233, v233
	v_rcp_f32_e32 v234, v234
	v_rcp_f32_e32 v235, v235
	v_fma_f32 v242, -v132, v247, v204
	v_fma_f32 v243, v132, v246, v220
	v_fma_f32 v244, v128, v246, v242
	v_fma_f32 v245, v128, v247, v243
	v_cvt_pk_bf16_f32 v248, v244, v245
	ds_write_b32 v149, v248 offset:13504
	v_pk_mul_f32 v[232:233], v[72:73], v[232:233]
	v_pk_mul_f32 v[234:235], v[74:75], v[234:235]
	v_cvt_pk_bf16_f32 v236, v232, v232
	v_fma_f32 v242, -v132, v245, v205
	v_fma_f32 v243, v132, v244, v221
	v_fma_f32 v246, v128, v244, v242
	v_fma_f32 v247, v128, v245, v243
	v_cvt_pk_bf16_f32 v249, v246, v247
	ds_write_b32 v149, v249 offset:13776
	v_cvt_pk_bf16_f32 v237, v233, v233
	v_cvt_pk_bf16_f32 v238, v234, v234
	v_cvt_pk_bf16_f32 v239, v235, v235
	v_fma_f32 v242, -v132, v247, v206
	v_fma_f32 v243, v132, v246, v222
	v_fma_f32 v244, v128, v246, v242
	v_fma_f32 v245, v128, v247, v243
	v_cvt_pk_bf16_f32 v248, v244, v245
	ds_write_b32 v149, v248 offset:14048
	ds_write_b16 v160, v236 offset:15616
	ds_write_b16 v160, v237 offset:15648
	ds_write_b16 v160, v238 offset:15680
	v_fma_f32 v242, -v132, v245, v207
	v_fma_f32 v243, v132, v244, v223
	v_fma_f32 v86, v128, v244, v242
	v_fma_f32 v87, v128, v245, v243
	v_cvt_pk_bf16_f32 v249, v86, v87
	ds_write_b32 v149, v249 offset:14320
	ds_write_b16 v163, v239 offset:14592
	s_waitcnt lgkmcnt(0)
	ds_read_b128 v[72:75], v80 offset:10240
	ds_read_b128 v[76:79], v80 offset:10304
	ds_read_b128 v[184:187], v80 offset:10368
	ds_read_b128 v[188:191], v80 offset:10432
	s_waitcnt lgkmcnt(3)
	v_mfma_f32_16x16x32_bf16 v[68:71], v[72:75], v[32:35], v[68:71]
	s_waitcnt lgkmcnt(2)
	v_mfma_f32_16x16x32_bf16 v[68:71], v[76:79], v[36:39], v[68:71]
	s_waitcnt vmcnt(3)
	v_mov_b64_e32 v[82:83], v[54:55]
	v_mov_b64_e32 v[80:81], v[52:53]
	s_waitcnt lgkmcnt(1)
	v_mfma_f32_16x16x32_bf16 v[68:71], v[184:187], v[40:43], v[68:71]
	s_waitcnt lgkmcnt(0)
	v_mfma_f32_16x16x32_bf16 v[68:71], v[188:191], v[44:47], v[68:71]
	s_waitcnt vmcnt(2)
	v_mov_b64_e32 v[78:79], v[58:59]
	v_mov_b64_e32 v[76:77], v[56:57]
	s_nop 4
	v_pk_mul_f32 v[232:233], v[68:69], v[224:225]
	v_pk_mul_f32 v[234:235], v[70:71], v[224:225]
	v_pk_fma_f32 v[232:233], v[68:69], v[232:233], v[226:227]
	v_pk_fma_f32 v[234:235], v[70:71], v[234:235], v[226:227]
	v_pk_mul_f32 v[232:233], v[68:69], v[232:233]
	v_pk_mul_f32 v[234:235], v[70:71], v[234:235]
	v_pk_mul_f32 v[232:233], v[232:233], v[228:229]
	v_pk_mul_f32 v[234:235], v[234:235], v[228:229]
	v_exp_f32_e32 v232, v232
	v_exp_f32_e32 v233, v233
	v_exp_f32_e32 v234, v234
	v_exp_f32_e32 v235, v235
	v_pk_add_f32 v[232:233], v[232:233], v[230:231]
	v_pk_add_f32 v[234:235], v[234:235], v[230:231]
	v_rcp_f32_e32 v232, v232
	v_rcp_f32_e32 v233, v233
	v_rcp_f32_e32 v234, v234
	v_rcp_f32_e32 v235, v235
	v_pk_mul_f32 v[232:233], v[68:69], v[232:233]
	v_pk_mul_f32 v[234:235], v[70:71], v[234:235]
	v_cvt_pk_bf16_f32 v236, v232, v232
	v_cvt_pk_bf16_f32 v237, v233, v233
	v_cvt_pk_bf16_f32 v238, v234, v234
	v_cvt_pk_bf16_f32 v239, v235, v235
	ds_write_b16 v160, v236 offset:16128
	ds_write_b16 v160, v237 offset:16160
	ds_write_b16 v160, v238 offset:16192
	ds_write_b16 v164, v239 offset:14592
	s_waitcnt vmcnt(1)
	v_mov_b64_e32 v[74:75], v[62:63]
	v_mov_b64_e32 v[72:73], v[60:61]
	s_waitcnt lgkmcnt(0)
	s_waitcnt vmcnt(0)
	v_mov_b64_e32 v[70:71], v[66:67]
	v_mov_b64_e32 v[68:69], v[64:65]
